# group-A: first P.V fragment reads issued before the P pack swaps and mid-tile barrier
# baseline (speedup 1.0000x reference)
.LskewA_in:
.LBB0_236:
	s_mov_b32 s40, s4
	v_mov_b32_e32 v68, 0
	s_waitcnt lgkmcnt(0)
	v_sub_u32_e32 v66, v254, v201
	v_cmp_lt_i32_e32 vcc, s87, v66
	v_cmp_gt_i32_e64 s[12:13], s84, v66
	s_and_saveexec_b64 s[4:5], s[12:13]
	v_mov_b32_e32 v66, s86
	ds_read_b32 v68, v66
	s_or_b64 exec, exec, s[4:5]
	global_load_dword v253, v[184:185], off
	s_lshl_b32 s45, s39, 14
	s_add_i32 s45, s45, s44
	s_add_i32 s48, s45, 0xc000
	s_mov_b32 m0, s48
	s_mov_b64 exec, s[8:9]
	s_add_i32 s48, s48, 0x2000
	global_load_lds_dwordx4 v[116:117], off
	s_mov_b32 m0, s48
	s_nop 0
	global_load_lds_dwordx4 v[118:119], off
	s_mov_b64 exec, -1
	v_lshl_add_u64 v[116:117], v[116:117], 0, s[62:63]
	v_lshl_add_u64 v[118:119], v[118:119], 0, s[62:63]
	s_lshl_b32 s43, s33, 14
	v_add_u32_e32 v66, s43, v221
	v_add_u32_e32 v67, v66, v210
	ds_read_b128 v[226:229], v67 offset:49152
	ds_read_b128 v[238:241], v67 offset:57344
	s_waitcnt lgkmcnt(2)
	v_mov_b32_e32 v69, v68
	v_mov_b32_e32 v70, v68
	v_mov_b32_e32 v71, v68
	v_mov_b32_e32 v72, v68
	v_mov_b32_e32 v73, v68
	v_mov_b32_e32 v74, v68
	v_mov_b32_e32 v75, v68
	v_mov_b32_e32 v76, v68
	v_mov_b32_e32 v77, v68
	v_mov_b32_e32 v78, v68
	v_mov_b32_e32 v79, v68
	v_mov_b32_e32 v80, v68
	v_mov_b32_e32 v81, v68
	v_mov_b32_e32 v82, v68
	v_mov_b32_e32 v83, v68
	v_add_u32_e32 v67, v66, v212
	v_exp_f32_e32 v219, v136
	s_waitcnt lgkmcnt(1)
	v_mfma_f32_32x32x16_bf16 v[84:99], v[226:229], v[100:103], v[68:83]
	v_exp_f32_e32 v130, v130
	v_exp_f32_e32 v131, v131
	v_exp_f32_e32 v128, v128
	v_exp_f32_e32 v129, v129
	v_exp_f32_e32 v126, v126
	v_exp_f32_e32 v127, v127
	v_exp_f32_e32 v124, v124
	s_waitcnt lgkmcnt(0)
	v_mfma_f32_32x32x16_bf16 v[68:83], v[238:241], v[100:103], v[68:83]
	ds_read_b128 v[226:229], v67 offset:49152
	ds_read_b128 v[238:241], v67 offset:57344
	v_add_u32_e32 v67, v66, v213
	v_add_u32_e32 v66, v66, v214
	v_exp_f32_e32 v125, v125
	s_waitcnt lgkmcnt(0)
	v_mfma_f32_32x32x16_bf16 v[68:83], v[238:241], v[104:107], v[68:83]
	v_mfma_f32_32x32x16_bf16 v[84:99], v[226:229], v[104:107], v[84:99]
	ds_read_b128 v[226:229], v67 offset:49152
	ds_read_b128 v[238:241], v67 offset:57344
	v_exp_f32_e32 v67, v139
	s_waitcnt lgkmcnt(0)
	v_mfma_f32_32x32x16_bf16 v[68:83], v[238:241], v[108:111], v[68:83]
	v_mfma_f32_32x32x16_bf16 v[84:99], v[226:229], v[108:111], v[84:99]
	ds_read_b128 v[226:229], v66 offset:49152
	ds_read_b128 v[238:241], v66 offset:57344
	v_exp_f32_e32 v66, v138
	s_waitcnt lgkmcnt(0)
	v_mfma_f32_32x32x16_bf16 v[68:83], v[238:241], v[112:115], v[68:83]
	v_exp_f32_e32 v238, v132
	v_add_f32_e32 v132, 0, v230
	v_add_f32_e32 v132, v234, v132
	v_add_f32_e32 v132, v231, v132
	v_add_f32_e32 v132, v235, v132
	v_add_f32_e32 v132, v232, v132
	v_add_f32_e32 v132, v236, v132
	v_add_f32_e32 v132, v233, v132
	v_add_f32_e32 v132, v237, v132
	v_add_f32_e32 v132, v140, v132
	v_add_f32_e32 v132, v143, v132
	v_add_f32_e32 v132, v141, v132
	v_add_f32_e32 v132, v144, v132
	v_add_f32_e32 v132, v142, v132
	v_add_f32_e32 v132, v146, v132
	v_add_f32_e32 v132, v145, v132
	v_mfma_f32_32x32x16_bf16 v[84:99], v[226:229], v[112:115], v[84:99]
	v_exp_f32_e32 v227, v137
	v_add_f32_e32 v132, v147, v132
	v_exp_f32_e32 v228, v134
	v_add_f32_e32 v132, v66, v132
	v_exp_f32_e32 v229, v135
	v_add_f32_e32 v132, v67, v132
	v_add_f32_e32 v132, v219, v132
	v_exp_f32_e32 v239, v133
	v_add_f32_e32 v132, v227, v132
	v_add_f32_e32 v132, v228, v132
	v_add_f32_e32 v132, v229, v132
	v_add_f32_e32 v132, v238, v132
	v_add_f32_e32 v132, v239, v132
	v_add_f32_e32 v132, v130, v132
	v_add_f32_e32 v132, v131, v132
	v_add_f32_e32 v132, v128, v132
	v_add_f32_e32 v132, v129, v132
	v_add_f32_e32 v132, v126, v132
	v_add_f32_e32 v132, v127, v132
	v_add_f32_e32 v132, v124, v132
	v_add_f32_e32 v225, v125, v132
	ds_bpermute_b32 v226, v187, v225
	v_cvt_pk_bf16_f32 v132, v230, v234
	v_cvt_pk_bf16_f32 v133, v231, v235
	v_cvt_pk_bf16_f32 v134, v232, v236
	v_cvt_pk_bf16_f32 v135, v233, v237
	v_cvt_pk_bf16_f32 v136, v140, v143
	v_cvt_pk_bf16_f32 v137, v141, v144
	v_cvt_pk_bf16_f32 v138, v142, v146
	v_cvt_pk_bf16_f32 v139, v145, v147
	v_cvt_pk_bf16_f32 v140, v66, v67
	v_cvt_pk_bf16_f32 v141, v219, v227
	v_cvt_pk_bf16_f32 v142, v228, v229
	v_cvt_pk_bf16_f32 v143, v238, v239
	v_cvt_pk_bf16_f32 v144, v130, v131
	v_cvt_pk_bf16_f32 v145, v128, v129
	v_cvt_pk_bf16_f32 v146, v126, v127
	v_cvt_pk_bf16_f32 v147, v124, v125
	s_nop 0
	s_lshl_b32 s42, s39, 14
	v_add_u32_e32 v219, s42, v188
	ds_read_b64_tr_b16 v[228:229], v219 offset:0
	ds_read_b64_tr_b16 v[230:231], v219 offset:0x800
	ds_read_b64_tr_b16 v[232:233], v219 offset:0x1000
	ds_read_b64_tr_b16 v[234:235], v219 offset:0x1800
	ds_read_b64_tr_b16 v[236:237], v219 offset:0x2000
	ds_read_b64_tr_b16 v[238:239], v219 offset:0x2800
	ds_read_b64_tr_b16 v[240:241], v219 offset:0x3000
	ds_read_b64_tr_b16 v[242:243], v219 offset:0x3800
	v_permlane32_swap_b32_e32 v132, v134
	v_permlane32_swap_b32_e32 v133, v135
	v_permlane32_swap_b32_e32 v136, v138
	v_permlane32_swap_b32_e32 v137, v139
	v_permlane32_swap_b32_e32 v140, v142
	v_permlane32_swap_b32_e32 v141, v143
	v_permlane32_swap_b32_e32 v144, v146
	v_permlane32_swap_b32_e32 v145, v147
	s_waitcnt vmcnt(2)
	s_barrier
	s_lshl_b32 s45, s40, 14
	s_add_i32 s45, s45, s44
	s_mov_b32 m0, s45
	s_add_i32 s45, s45, 0x2000
	global_load_lds_dwordx4 v[120:121], off
	s_mov_b32 m0, s45
	v_lshl_add_u64 v[120:121], v[120:121], 0, s[62:63]
	global_load_lds_dwordx4 v[122:123], off
	v_lshl_add_u64 v[122:123], v[122:123], 0, s[62:63]
	s_waitcnt lgkmcnt(0)
	s_nop 0
	v_mfma_f32_32x32x16_bf16 v[50:65], v[132:135], v[228:231], v[50:65]
	ds_read_b64_tr_b16 v[228:229], v219 offset:0x200
	ds_read_b64_tr_b16 v[230:231], v219 offset:0xa00
	v_mfma_f32_32x32x16_bf16 v[50:65], v[136:139], v[232:235], v[50:65]
	ds_read_b64_tr_b16 v[232:233], v219 offset:0x1200
	ds_read_b64_tr_b16 v[234:235], v219 offset:0x1a00
	v_mfma_f32_32x32x16_bf16 v[50:65], v[140:143], v[236:239], v[50:65]
	ds_read_b64_tr_b16 v[236:237], v219 offset:0x2200
	ds_read_b64_tr_b16 v[238:239], v219 offset:0x2a00
	v_mfma_f32_32x32x16_bf16 v[50:65], v[144:147], v[240:243], v[50:65]
	ds_read_b64_tr_b16 v[240:241], v219 offset:0x3200
	ds_read_b64_tr_b16 v[242:243], v219 offset:0x3a00
	s_waitcnt lgkmcnt(0)
	v_mfma_f32_32x32x16_bf16 v[34:49], v[132:135], v[228:231], v[34:49]
	ds_read_b64_tr_b16 v[228:229], v219 offset:0x400
	ds_read_b64_tr_b16 v[230:231], v219 offset:0xc00
	v_mfma_f32_32x32x16_bf16 v[34:49], v[136:139], v[232:235], v[34:49]
	ds_read_b64_tr_b16 v[232:233], v219 offset:0x1400
	ds_read_b64_tr_b16 v[234:235], v219 offset:0x1c00
	v_mfma_f32_32x32x16_bf16 v[34:49], v[140:143], v[236:239], v[34:49]
	ds_read_b64_tr_b16 v[236:237], v219 offset:0x2400
	ds_read_b64_tr_b16 v[238:239], v219 offset:0x2c00
	v_mfma_f32_32x32x16_bf16 v[34:49], v[144:147], v[240:243], v[34:49]
	ds_read_b64_tr_b16 v[240:241], v219 offset:0x3400
	ds_read_b64_tr_b16 v[242:243], v219 offset:0x3c00
	s_waitcnt lgkmcnt(0)
	v_mfma_f32_32x32x16_bf16 v[18:33], v[132:135], v[228:231], v[18:33]
	ds_read_b64_tr_b16 v[228:229], v219 offset:0x600
	ds_read_b64_tr_b16 v[230:231], v219 offset:0xe00
	v_mfma_f32_32x32x16_bf16 v[18:33], v[136:139], v[232:235], v[18:33]
	ds_read_b64_tr_b16 v[232:233], v219 offset:0x1600
	ds_read_b64_tr_b16 v[234:235], v219 offset:0x1e00
	v_mfma_f32_32x32x16_bf16 v[18:33], v[140:143], v[236:239], v[18:33]
	ds_read_b64_tr_b16 v[236:237], v219 offset:0x2600
	ds_read_b64_tr_b16 v[238:239], v219 offset:0x2e00
	v_mfma_f32_32x32x16_bf16 v[18:33], v[144:147], v[240:243], v[18:33]
	ds_read_b64_tr_b16 v[240:241], v219 offset:0x3600
	ds_read_b64_tr_b16 v[242:243], v219 offset:0x3e00
	s_waitcnt lgkmcnt(0)
	v_mfma_f32_32x32x16_bf16 v[2:17], v[132:135], v[228:231], v[2:17]
	v_mfma_f32_32x32x16_bf16 v[2:17], v[136:139], v[232:235], v[2:17]
	v_mfma_f32_32x32x16_bf16 v[2:17], v[140:143], v[236:239], v[2:17]
	v_mfma_f32_32x32x16_bf16 v[2:17], v[144:147], v[240:243], v[2:17]
	s_and_saveexec_b64 s[4:5], vcc
	s_cbranch_execz .LBB0_242
	flat_load_dwordx4 v[132:135], v[182:183] offset:256
	flat_load_dwordx4 v[136:139], v[182:183] offset:384
	flat_load_dwordx4 v[140:143], v[182:183] offset:288
	flat_load_dwordx4 v[144:147], v[182:183] offset:416
	flat_load_dwordx4 v[228:231], v[182:183] offset:320
	flat_load_dwordx4 v[232:235], v[182:183] offset:448
	flat_load_dwordx4 v[236:239], v[182:183] offset:352
	flat_load_dwordx4 v[240:243], v[182:183] offset:480
	s_waitcnt vmcnt(0) lgkmcnt(0)
	v_sub_u32_e32 v66, v132, v167
	v_sub_u32_e32 v67, v136, v167
	v_sub_u32_e32 v132, v133, v167
	v_sub_u32_e32 v133, v137, v167
	v_sub_u32_e32 v134, v134, v167
	v_sub_u32_e32 v136, v138, v167
	v_sub_u32_e32 v135, v135, v167
	v_sub_u32_e32 v137, v139, v167
	v_sub_u32_e32 v138, v140, v167
	v_sub_u32_e32 v139, v144, v167
	v_sub_u32_e32 v140, v141, v167
	v_sub_u32_e32 v141, v145, v167
	v_sub_u32_e32 v142, v142, v167
	v_sub_u32_e32 v144, v146, v167
	v_sub_u32_e32 v143, v143, v167
	v_sub_u32_e32 v145, v147, v167
	v_sub_u32_e32 v146, v228, v167
	v_sub_u32_e32 v228, v233, v167
	v_med3_i32 v66, v66, s87, v197
	v_med3_i32 v67, v67, s87, v197
	v_med3_i32 v132, v132, s87, v197
	v_med3_i32 v133, v133, s87, v197
	v_med3_i32 v134, v134, s87, v197
	v_med3_i32 v136, v136, s87, v197
	v_med3_i32 v135, v135, s87, v197
	v_med3_i32 v137, v137, s87, v197
	v_med3_i32 v138, v138, s87, v197
	v_med3_i32 v139, v139, s87, v197
	v_med3_i32 v141, v141, s87, v197
	v_med3_i32 v142, v142, s87, v197
	v_med3_i32 v144, v144, s87, v197
	v_med3_i32 v143, v143, s87, v197
	v_med3_i32 v145, v145, s87, v197
	v_sub_u32_e32 v227, v229, v167
	v_med3_i32 v140, v140, s87, v197
	v_med3_i32 v228, v228, s87, v197
	v_lshl_add_u32 v66, v66, 2, s86
	v_lshl_add_u32 v67, v67, 2, s86
	v_lshl_add_u32 v229, v132, 2, s86
	v_lshl_add_u32 v133, v133, 2, s86
	v_lshl_add_u32 v134, v134, 2, s86
	v_lshl_add_u32 v136, v136, 2, s86
	v_lshl_add_u32 v135, v135, 2, s86
	v_lshl_add_u32 v137, v137, 2, s86
	v_lshl_add_u32 v138, v138, 2, s86
	v_lshl_add_u32 v139, v139, 2, s86
	v_lshl_add_u32 v141, v141, 2, s86
	v_lshl_add_u32 v142, v142, 2, s86
	v_lshl_add_u32 v144, v144, 2, s86
	v_lshl_add_u32 v143, v143, 2, s86
	v_lshl_add_u32 v145, v145, 2, s86
	v_sub_u32_e32 v147, v232, v167
	v_lshl_add_u32 v232, v140, 2, s86
	v_lshl_add_u32 v233, v228, 2, s86
	ds_read_b32 v66, v66 offset:1220
	ds_read_b32 v132, v67 offset:1220
	ds_read_b32 v67, v229 offset:1220
	ds_read_b32 v133, v133 offset:1220
	ds_read_b32 v134, v134 offset:1220
	ds_read_b32 v136, v136 offset:1220
	ds_read_b32 v135, v135 offset:1220
	ds_read_b32 v137, v137 offset:1220
	ds_read_b32 v138, v138 offset:1220
	ds_read_b32 v140, v139 offset:1220
	ds_read_b32 v139, v232 offset:1220
	ds_read_b32 v141, v141 offset:1220
	ds_read_b32 v142, v142 offset:1220
	ds_read_b32 v144, v144 offset:1220
	ds_read_b32 v143, v143 offset:1220
	ds_read_b32 v145, v145 offset:1220
	v_sub_u32_e32 v228, v230, v167
	v_sub_u32_e32 v229, v234, v167
	v_med3_i32 v228, v228, s87, v197
	v_med3_i32 v229, v229, s87, v197
	v_lshl_add_u32 v230, v228, 2, s86
	v_lshl_add_u32 v232, v229, 2, s86
	v_sub_u32_e32 v228, v231, v167
	v_sub_u32_e32 v229, v235, v167
	v_med3_i32 v146, v146, s87, v197
	v_med3_i32 v147, v147, s87, v197
	v_med3_i32 v228, v228, s87, v197
	v_med3_i32 v229, v229, s87, v197
	v_med3_i32 v227, v227, s87, v197
	v_lshl_add_u32 v146, v146, 2, s86
	v_lshl_add_u32 v147, v147, 2, s86
	v_lshl_add_u32 v231, v228, 2, s86
	v_lshl_add_u32 v234, v229, 2, s86
	v_lshl_add_u32 v227, v227, 2, s86
	ds_read_b32 v146, v146 offset:1220
	ds_read_b32 v228, v147 offset:1220
	ds_read_b32 v147, v227 offset:1220
	ds_read_b32 v229, v233 offset:1220
	ds_read_b32 v230, v230 offset:1220
	ds_read_b32 v232, v232 offset:1220
	ds_read_b32 v231, v231 offset:1220
	ds_read_b32 v233, v234 offset:1220
	v_sub_u32_e32 v234, v240, v167
	v_med3_i32 v234, v234, s87, v197
	v_sub_u32_e32 v227, v236, v167
	v_lshl_add_u32 v235, v234, 2, s86
	v_sub_u32_e32 v234, v237, v167
	v_sub_u32_e32 v236, v241, v167
	v_med3_i32 v234, v234, s87, v197
	v_med3_i32 v236, v236, s87, v197
	v_lshl_add_u32 v237, v234, 2, s86
	v_lshl_add_u32 v244, v236, 2, s86
	v_sub_u32_e32 v234, v238, v167
	v_sub_u32_e32 v236, v242, v167
	v_med3_i32 v234, v234, s87, v197
	v_med3_i32 v236, v236, s87, v197
	v_lshl_add_u32 v238, v234, 2, s86
	v_lshl_add_u32 v240, v236, 2, s86
	v_sub_u32_e32 v234, v239, v167
	v_sub_u32_e32 v236, v243, v167
	v_med3_i32 v227, v227, s87, v197
	v_med3_i32 v234, v234, s87, v197
	v_med3_i32 v236, v236, s87, v197
	v_lshl_add_u32 v227, v227, 2, s86
	v_lshl_add_u32 v239, v234, 2, s86
	v_lshl_add_u32 v241, v236, 2, s86
	ds_read_b32 v234, v227 offset:1220
	ds_read_b32 v236, v235 offset:1220
	ds_read_b32 v238, v238 offset:1220
	ds_read_b32 v239, v239 offset:1220
	ds_read_b32 v235, v237 offset:1220
	ds_read_b32 v241, v241 offset:1220
	ds_read_b32 v240, v240 offset:1220
	ds_read_b32 v237, v244 offset:1220
	s_waitcnt lgkmcnt(4)
	v_pk_add_f32 v[98:99], v[98:99], v[238:239]
	s_waitcnt lgkmcnt(3)
	v_pk_add_f32 v[96:97], v[96:97], v[234:235]
	v_pk_add_f32 v[94:95], v[94:95], v[230:231]
	v_pk_add_f32 v[92:93], v[92:93], v[146:147]
	v_pk_add_f32 v[90:91], v[90:91], v[142:143]
	v_pk_add_f32 v[88:89], v[88:89], v[138:139]
	v_pk_add_f32 v[86:87], v[86:87], v[134:135]
	v_pk_add_f32 v[84:85], v[84:85], v[66:67]
	s_waitcnt lgkmcnt(1)
	v_pk_add_f32 v[82:83], v[82:83], v[240:241]
	s_waitcnt lgkmcnt(0)
	v_pk_add_f32 v[80:81], v[80:81], v[236:237]
	v_pk_add_f32 v[78:79], v[78:79], v[232:233]
	v_pk_add_f32 v[76:77], v[76:77], v[228:229]
	v_pk_add_f32 v[74:75], v[74:75], v[144:145]
	v_pk_add_f32 v[72:73], v[72:73], v[140:141]
	v_pk_add_f32 v[70:71], v[70:71], v[136:137]
	v_pk_add_f32 v[68:69], v[68:69], v[132:133]

.LBB0_248:
	s_waitcnt lgkmcnt(0)
	s_barrier
	s_waitcnt lgkmcnt(0)
	v_sub_u32_e32 v66, v253, v201
	v_cmp_lt_i32_e32 vcc, s87, v66
	v_cmp_gt_i32_e64 s[14:15], s84, v66
	v_mov_b32_e32 v66, 0
	s_and_saveexec_b64 s[4:5], s[14:15]
	v_mov_b32_e32 v66, s86
	ds_read_b32 v66, v66
	s_or_b64 exec, exec, s[4:5]
	global_load_dword v254, v[184:185], off offset:4
	s_lshl_b32 s45, s33, 14
	s_add_i32 s45, s45, s44
	s_add_i32 s48, s45, 0xc000
	s_mov_b32 m0, s48
	s_mov_b64 exec, s[8:9]
	s_add_i32 s48, s48, 0x2000
	global_load_lds_dwordx4 v[116:117], off
	s_mov_b32 m0, s48
	s_nop 0
	global_load_lds_dwordx4 v[118:119], off
	s_mov_b64 exec, -1
	v_lshl_add_u64 v[116:117], v[116:117], 0, s[62:63]
	v_lshl_add_u64 v[118:119], v[118:119], 0, s[62:63]
	v_cndmask_b32_e64 v224, v67, v224, s[12:13]
	v_mul_f32_e32 v132, 0xbe38aa3b, v224
	v_fmamk_f32 v138, v99, 0x3e38aa3b, v132
	v_exp_f32_e32 v139, v138
	v_add_u32_e32 v138, s41, v221
	v_fmamk_f32 v242, v82, 0x3e38aa3b, v132
	v_add_u32_e32 v82, v138, v210
	ds_read_b128 v[140:143], v82 offset:49152
	ds_read_b128 v[144:147], v82 offset:57344
	v_fmamk_f32 v67, v84, 0x3e38aa3b, v132
	v_fmamk_f32 v84, v85, 0x3e38aa3b, v132
	v_fmamk_f32 v85, v86, 0x3e38aa3b, v132
	v_fmamk_f32 v86, v87, 0x3e38aa3b, v132
	v_fmamk_f32 v87, v88, 0x3e38aa3b, v132
	v_fmamk_f32 v88, v89, 0x3e38aa3b, v132
	v_fmamk_f32 v89, v90, 0x3e38aa3b, v132
	v_fmamk_f32 v90, v91, 0x3e38aa3b, v132
	v_fmamk_f32 v91, v92, 0x3e38aa3b, v132
	v_fmamk_f32 v92, v93, 0x3e38aa3b, v132
	v_fmamk_f32 v93, v94, 0x3e38aa3b, v132
	v_fmamk_f32 v94, v95, 0x3e38aa3b, v132
	v_fmamk_f32 v95, v96, 0x3e38aa3b, v132
	v_fmamk_f32 v96, v97, 0x3e38aa3b, v132
	v_fmamk_f32 v97, v98, 0x3e38aa3b, v132
	v_fmamk_f32 v228, v68, 0x3e38aa3b, v132
	v_fmamk_f32 v229, v69, 0x3e38aa3b, v132
	v_fmamk_f32 v230, v70, 0x3e38aa3b, v132
	v_fmamk_f32 v231, v71, 0x3e38aa3b, v132
	v_fmamk_f32 v232, v72, 0x3e38aa3b, v132
	v_fmamk_f32 v233, v73, 0x3e38aa3b, v132
	v_fmamk_f32 v234, v74, 0x3e38aa3b, v132
	v_fmamk_f32 v235, v75, 0x3e38aa3b, v132
	v_fmamk_f32 v236, v76, 0x3e38aa3b, v132
	v_fmamk_f32 v237, v77, 0x3e38aa3b, v132
	v_fmamk_f32 v238, v78, 0x3e38aa3b, v132
	v_fmamk_f32 v239, v79, 0x3e38aa3b, v132
	v_fmamk_f32 v240, v80, 0x3e38aa3b, v132
	v_fmamk_f32 v241, v81, 0x3e38aa3b, v132
	v_exp_f32_e32 v125, v67
	s_waitcnt lgkmcnt(2)
	v_mov_b32_e32 v67, v66
	v_mov_b32_e32 v68, v66
	v_mov_b32_e32 v69, v66
	v_mov_b32_e32 v70, v66
	v_mov_b32_e32 v71, v66
	v_mov_b32_e32 v72, v66
	v_mov_b32_e32 v73, v66
	v_mov_b32_e32 v74, v66
	v_mov_b32_e32 v75, v66
	v_mov_b32_e32 v76, v66
	v_mov_b32_e32 v77, v66
	v_mov_b32_e32 v78, v66
	v_mov_b32_e32 v79, v66
	v_mov_b32_e32 v80, v66
	v_mov_b32_e32 v81, v66
	v_fmac_f32_e32 v132, 0x3e38aa3b, v83
	v_exp_f32_e32 v128, v84
	v_exp_f32_e32 v129, v85
	v_exp_f32_e32 v133, v86
	v_exp_f32_e32 v134, v87
	v_exp_f32_e32 v135, v88
	v_exp_f32_e32 v136, v89
	v_exp_f32_e32 v137, v90
	v_exp_f32_e32 v98, v91
	v_exp_f32_e32 v99, v92
	v_exp_f32_e32 v124, v93
	v_exp_f32_e32 v126, v94
	v_exp_f32_e32 v127, v95
	v_exp_f32_e32 v130, v96
	v_exp_f32_e32 v131, v97
	s_waitcnt lgkmcnt(1)
	v_mfma_f32_32x32x16_bf16 v[82:97], v[140:143], v[100:103], v[66:81]
	s_waitcnt lgkmcnt(0)
	v_mfma_f32_32x32x16_bf16 v[66:81], v[144:147], v[100:103], v[66:81]
	v_add_u32_e32 v144, v138, v212
	ds_read_b128 v[140:143], v144 offset:49152
	ds_read_b128 v[144:147], v144 offset:57344
	s_waitcnt lgkmcnt(1)
	v_mfma_f32_32x32x16_bf16 v[82:97], v[140:143], v[104:107], v[82:97]
	s_waitcnt lgkmcnt(0)
	v_mfma_f32_32x32x16_bf16 v[66:81], v[144:147], v[104:107], v[66:81]
	v_add_u32_e32 v144, v138, v213
	ds_read_b128 v[140:143], v144 offset:49152
	ds_read_b128 v[144:147], v144 offset:57344
	v_add_u32_e32 v138, v138, v214
	s_waitcnt lgkmcnt(1)
	v_mfma_f32_32x32x16_bf16 v[82:97], v[140:143], v[108:111], v[82:97]
	s_waitcnt lgkmcnt(0)
	v_mfma_f32_32x32x16_bf16 v[66:81], v[144:147], v[108:111], v[66:81]
	ds_read_b128 v[140:143], v138 offset:49152
	ds_read_b128 v[144:147], v138 offset:57344
	s_waitcnt lgkmcnt(1)
	v_mfma_f32_32x32x16_bf16 v[82:97], v[140:143], v[112:115], v[82:97]
	v_exp_f32_e32 v143, v231
	v_exp_f32_e32 v231, v237
	v_exp_f32_e32 v237, v132
	v_add_f32_e32 v132, 0, v125
	v_add_f32_e32 v132, v128, v132
	v_add_f32_e32 v132, v129, v132
	v_add_f32_e32 v132, v133, v132
	v_add_f32_e32 v132, v134, v132
	v_add_f32_e32 v132, v135, v132
	v_add_f32_e32 v132, v136, v132
	v_add_f32_e32 v132, v137, v132
	v_add_f32_e32 v132, v98, v132
	v_add_f32_e32 v132, v99, v132
	v_add_f32_e32 v132, v124, v132
	v_add_f32_e32 v132, v126, v132
	v_exp_f32_e32 v140, v228
	v_add_f32_e32 v132, v127, v132
	v_exp_f32_e32 v141, v229
	v_add_f32_e32 v132, v130, v132
	v_exp_f32_e32 v142, v230
	v_add_f32_e32 v132, v131, v132
	v_add_f32_e32 v132, v139, v132
	s_waitcnt lgkmcnt(0)
	v_mfma_f32_32x32x16_bf16 v[66:81], v[144:147], v[112:115], v[66:81]
	v_exp_f32_e32 v144, v232
	v_add_f32_e32 v132, v140, v132
	v_exp_f32_e32 v145, v233
	v_add_f32_e32 v132, v141, v132
	v_exp_f32_e32 v146, v234
	v_add_f32_e32 v132, v142, v132
	v_exp_f32_e32 v147, v235
	v_add_f32_e32 v132, v143, v132
	v_exp_f32_e32 v230, v236
	v_add_f32_e32 v132, v144, v132
	v_add_f32_e32 v132, v145, v132
	v_exp_f32_e32 v232, v238
	v_add_f32_e32 v132, v146, v132
	v_exp_f32_e32 v233, v239
	v_add_f32_e32 v132, v147, v132
	v_exp_f32_e32 v234, v240
	v_add_f32_e32 v132, v230, v132
	v_exp_f32_e32 v235, v241
	v_add_f32_e32 v132, v231, v132
	v_exp_f32_e32 v236, v242
	v_add_f32_e32 v132, v232, v132
	v_add_f32_e32 v132, v233, v132
	v_add_f32_e32 v132, v234, v132
	v_add_f32_e32 v132, v235, v132
	v_add_f32_e32 v132, v236, v132
	v_add_f32_e32 v228, v237, v132
	ds_bpermute_b32 v229, v187, v228
	v_cvt_pk_bf16_f32 v132, v125, v128
	v_cvt_pk_bf16_f32 v133, v129, v133
	v_cvt_pk_bf16_f32 v134, v134, v135
	v_cvt_pk_bf16_f32 v135, v136, v137
	v_cvt_pk_bf16_f32 v136, v98, v99
	v_cvt_pk_bf16_f32 v137, v124, v126
	v_cvt_pk_bf16_f32 v138, v127, v130
	v_cvt_pk_bf16_f32 v139, v131, v139
	v_cvt_pk_bf16_f32 v140, v140, v141
	v_cvt_pk_bf16_f32 v141, v142, v143
	v_cvt_pk_bf16_f32 v142, v144, v145
	v_cvt_pk_bf16_f32 v143, v146, v147
	v_cvt_pk_bf16_f32 v144, v230, v231
	v_cvt_pk_bf16_f32 v145, v232, v233
	v_cvt_pk_bf16_f32 v146, v234, v235
	v_cvt_pk_bf16_f32 v147, v236, v237
	s_nop 0
	v_add_u32_e32 v98, s43, v188
	ds_read_b64_tr_b16 v[230:231], v98 offset:0
	ds_read_b64_tr_b16 v[232:233], v98 offset:0x800
	ds_read_b64_tr_b16 v[234:235], v98 offset:0x1000
	ds_read_b64_tr_b16 v[236:237], v98 offset:0x1800
	ds_read_b64_tr_b16 v[238:239], v98 offset:0x2000
	ds_read_b64_tr_b16 v[240:241], v98 offset:0x2800
	ds_read_b64_tr_b16 v[242:243], v98 offset:0x3000
	ds_read_b64_tr_b16 v[244:245], v98 offset:0x3800
	v_permlane32_swap_b32_e32 v132, v134
	v_permlane32_swap_b32_e32 v133, v135
	v_permlane32_swap_b32_e32 v136, v138
	v_permlane32_swap_b32_e32 v137, v139
	v_permlane32_swap_b32_e32 v140, v142
	v_permlane32_swap_b32_e32 v141, v143
	v_permlane32_swap_b32_e32 v144, v146
	v_permlane32_swap_b32_e32 v145, v147
	s_waitcnt vmcnt(2)
	s_barrier
	s_lshl_b32 s45, s39, 14
	s_add_i32 s45, s45, s44
	s_mov_b32 m0, s45
	s_add_i32 s45, s45, 0x2000
	global_load_lds_dwordx4 v[120:121], off
	s_mov_b32 m0, s45
	v_lshl_add_u64 v[120:121], v[120:121], 0, s[62:63]
	global_load_lds_dwordx4 v[122:123], off
	v_lshl_add_u64 v[122:123], v[122:123], 0, s[62:63]
	s_waitcnt lgkmcnt(0)
	s_nop 0
	v_mfma_f32_32x32x16_bf16 v[50:65], v[132:135], v[230:233], v[50:65]
	ds_read_b64_tr_b16 v[230:231], v98 offset:0x200
	ds_read_b64_tr_b16 v[232:233], v98 offset:0xa00
	v_mfma_f32_32x32x16_bf16 v[50:65], v[136:139], v[234:237], v[50:65]
	ds_read_b64_tr_b16 v[234:235], v98 offset:0x1200
	ds_read_b64_tr_b16 v[236:237], v98 offset:0x1a00
	v_mfma_f32_32x32x16_bf16 v[50:65], v[140:143], v[238:241], v[50:65]
	ds_read_b64_tr_b16 v[238:239], v98 offset:0x2200
	ds_read_b64_tr_b16 v[240:241], v98 offset:0x2a00
	v_mfma_f32_32x32x16_bf16 v[50:65], v[144:147], v[242:245], v[50:65]
	ds_read_b64_tr_b16 v[242:243], v98 offset:0x3200
	ds_read_b64_tr_b16 v[244:245], v98 offset:0x3a00
	s_waitcnt lgkmcnt(0)
	v_mfma_f32_32x32x16_bf16 v[34:49], v[132:135], v[230:233], v[34:49]
	ds_read_b64_tr_b16 v[230:231], v98 offset:0x400
	ds_read_b64_tr_b16 v[232:233], v98 offset:0xc00
	v_mfma_f32_32x32x16_bf16 v[34:49], v[136:139], v[234:237], v[34:49]
	ds_read_b64_tr_b16 v[234:235], v98 offset:0x1400
	ds_read_b64_tr_b16 v[236:237], v98 offset:0x1c00
	v_mfma_f32_32x32x16_bf16 v[34:49], v[140:143], v[238:241], v[34:49]
	ds_read_b64_tr_b16 v[238:239], v98 offset:0x2400
	ds_read_b64_tr_b16 v[240:241], v98 offset:0x2c00
	v_mfma_f32_32x32x16_bf16 v[34:49], v[144:147], v[242:245], v[34:49]
	ds_read_b64_tr_b16 v[242:243], v98 offset:0x3400
	ds_read_b64_tr_b16 v[244:245], v98 offset:0x3c00
	s_waitcnt lgkmcnt(0)
	v_mfma_f32_32x32x16_bf16 v[18:33], v[132:135], v[230:233], v[18:33]
	ds_read_b64_tr_b16 v[230:231], v98 offset:0x600
	ds_read_b64_tr_b16 v[232:233], v98 offset:0xe00
	v_mfma_f32_32x32x16_bf16 v[18:33], v[136:139], v[234:237], v[18:33]
	ds_read_b64_tr_b16 v[234:235], v98 offset:0x1600
	ds_read_b64_tr_b16 v[236:237], v98 offset:0x1e00
	v_mfma_f32_32x32x16_bf16 v[18:33], v[140:143], v[238:241], v[18:33]
	ds_read_b64_tr_b16 v[238:239], v98 offset:0x2600
	ds_read_b64_tr_b16 v[240:241], v98 offset:0x2e00
	v_mfma_f32_32x32x16_bf16 v[18:33], v[144:147], v[242:245], v[18:33]
	ds_read_b64_tr_b16 v[242:243], v98 offset:0x3600
	ds_read_b64_tr_b16 v[244:245], v98 offset:0x3e00
	s_waitcnt lgkmcnt(0)
	v_mfma_f32_32x32x16_bf16 v[2:17], v[132:135], v[230:233], v[2:17]
	v_mfma_f32_32x32x16_bf16 v[2:17], v[136:139], v[234:237], v[2:17]
	v_mfma_f32_32x32x16_bf16 v[2:17], v[140:143], v[238:241], v[2:17]
	v_mfma_f32_32x32x16_bf16 v[2:17], v[144:147], v[242:245], v[2:17]
	s_and_saveexec_b64 s[4:5], vcc
	s_cbranch_execz .LBB0_254
	flat_load_dwordx4 v[132:135], v[182:183] offset:512
	flat_load_dwordx4 v[136:139], v[182:183] offset:640
	flat_load_dwordx4 v[140:143], v[182:183] offset:544
	flat_load_dwordx4 v[144:147], v[182:183] offset:672
	flat_load_dwordx4 v[230:233], v[182:183] offset:576
	flat_load_dwordx4 v[234:237], v[182:183] offset:704
	flat_load_dwordx4 v[238:241], v[182:183] offset:608
	flat_load_dwordx4 v[242:245], v[182:183] offset:736
	s_waitcnt vmcnt(0) lgkmcnt(0)
	v_sub_u32_e32 v98, v132, v167
	v_sub_u32_e32 v132, v133, v167
	v_sub_u32_e32 v133, v137, v167
	v_sub_u32_e32 v137, v139, v167
	v_sub_u32_e32 v139, v144, v167
	v_sub_u32_e32 v144, v146, v167
	v_sub_u32_e32 v146, v230, v167
	v_sub_u32_e32 v230, v231, v167
	v_sub_u32_e32 v99, v136, v167
	v_sub_u32_e32 v134, v134, v167
	v_sub_u32_e32 v136, v138, v167
	v_sub_u32_e32 v135, v135, v167
	v_sub_u32_e32 v138, v140, v167
	v_sub_u32_e32 v140, v141, v167
	v_sub_u32_e32 v141, v145, v167
	v_sub_u32_e32 v142, v142, v167
	v_sub_u32_e32 v143, v143, v167
	v_sub_u32_e32 v145, v147, v167
	v_med3_i32 v230, v230, s87, v197
	v_med3_i32 v98, v98, s87, v197
	v_med3_i32 v99, v99, s87, v197
	v_med3_i32 v132, v132, s87, v197
	v_med3_i32 v133, v133, s87, v197
	v_med3_i32 v134, v134, s87, v197
	v_med3_i32 v136, v136, s87, v197
	v_med3_i32 v135, v135, s87, v197
	v_med3_i32 v137, v137, s87, v197
	v_med3_i32 v138, v138, s87, v197
	v_med3_i32 v139, v139, s87, v197
	v_med3_i32 v140, v140, s87, v197
	v_med3_i32 v141, v141, s87, v197
	v_med3_i32 v142, v142, s87, v197
	v_med3_i32 v144, v144, s87, v197
	v_med3_i32 v143, v143, s87, v197
	v_med3_i32 v145, v145, s87, v197
	v_lshl_add_u32 v246, v230, 2, s86
	v_sub_u32_e32 v230, v232, v167
	v_sub_u32_e32 v232, v236, v167
	v_sub_u32_e32 v147, v234, v167
	v_sub_u32_e32 v231, v235, v167
	v_lshl_add_u32 v98, v98, 2, s86
	v_lshl_add_u32 v99, v99, 2, s86
	v_lshl_add_u32 v234, v132, 2, s86
	v_lshl_add_u32 v133, v133, 2, s86
	v_lshl_add_u32 v134, v134, 2, s86
	v_lshl_add_u32 v136, v136, 2, s86
	v_lshl_add_u32 v135, v135, 2, s86
	v_lshl_add_u32 v137, v137, 2, s86
	v_lshl_add_u32 v138, v138, 2, s86
	v_lshl_add_u32 v139, v139, 2, s86
	v_lshl_add_u32 v235, v140, 2, s86
	v_lshl_add_u32 v141, v141, 2, s86
	v_lshl_add_u32 v142, v142, 2, s86
	v_lshl_add_u32 v144, v144, 2, s86
	v_lshl_add_u32 v143, v143, 2, s86
	v_lshl_add_u32 v145, v145, 2, s86
	v_med3_i32 v230, v230, s87, v197
	v_med3_i32 v232, v232, s87, v197
	ds_read_b32 v98, v98 offset:1220
	ds_read_b32 v132, v99 offset:1220
	ds_read_b32 v99, v234 offset:1220
	ds_read_b32 v133, v133 offset:1220
	ds_read_b32 v134, v134 offset:1220
	ds_read_b32 v136, v136 offset:1220
	ds_read_b32 v135, v135 offset:1220
	ds_read_b32 v137, v137 offset:1220
	ds_read_b32 v138, v138 offset:1220
	ds_read_b32 v140, v139 offset:1220
	ds_read_b32 v139, v235 offset:1220
	ds_read_b32 v141, v141 offset:1220
	ds_read_b32 v142, v142 offset:1220
	ds_read_b32 v144, v144 offset:1220
	ds_read_b32 v143, v143 offset:1220
	ds_read_b32 v145, v145 offset:1220
	v_lshl_add_u32 v234, v230, 2, s86
	v_lshl_add_u32 v235, v232, 2, s86
	v_sub_u32_e32 v230, v233, v167
	v_sub_u32_e32 v232, v237, v167
	v_med3_i32 v146, v146, s87, v197
	v_med3_i32 v147, v147, s87, v197
	v_med3_i32 v231, v231, s87, v197
	v_med3_i32 v230, v230, s87, v197
	v_med3_i32 v232, v232, s87, v197
	v_lshl_add_u32 v146, v146, 2, s86
	v_lshl_add_u32 v147, v147, 2, s86
	v_lshl_add_u32 v231, v231, 2, s86
	v_lshl_add_u32 v233, v230, 2, s86
	v_lshl_add_u32 v236, v232, 2, s86
	ds_read_b32 v146, v146 offset:1220
	ds_read_b32 v230, v147 offset:1220
	ds_read_b32 v147, v246 offset:1220
	ds_read_b32 v231, v231 offset:1220
	ds_read_b32 v232, v234 offset:1220
	ds_read_b32 v234, v235 offset:1220
	ds_read_b32 v233, v233 offset:1220
	ds_read_b32 v235, v236 offset:1220
	v_sub_u32_e32 v236, v238, v167
	v_sub_u32_e32 v238, v239, v167
	v_med3_i32 v238, v238, s87, v197
	v_sub_u32_e32 v237, v242, v167
	v_lshl_add_u32 v242, v238, 2, s86
	v_sub_u32_e32 v238, v240, v167
	v_med3_i32 v238, v238, s87, v197
	v_sub_u32_e32 v240, v244, v167
	v_sub_u32_e32 v239, v243, v167
	v_med3_i32 v240, v240, s87, v197
	v_lshl_add_u32 v243, v238, 2, s86
	v_sub_u32_e32 v238, v241, v167
	v_med3_i32 v236, v236, s87, v197
	v_med3_i32 v237, v237, s87, v197
	v_med3_i32 v239, v239, s87, v197
	v_lshl_add_u32 v244, v240, 2, s86
	v_med3_i32 v238, v238, s87, v197
	v_sub_u32_e32 v240, v245, v167
	v_lshl_add_u32 v236, v236, 2, s86
	v_lshl_add_u32 v237, v237, 2, s86
	v_lshl_add_u32 v239, v239, 2, s86
	v_med3_i32 v240, v240, s87, v197
	v_lshl_add_u32 v241, v238, 2, s86
	v_lshl_add_u32 v245, v240, 2, s86
	ds_read_b32 v236, v236 offset:1220
	ds_read_b32 v238, v237 offset:1220
	ds_read_b32 v240, v243 offset:1220
	ds_read_b32 v241, v241 offset:1220
	ds_read_b32 v237, v242 offset:1220
	ds_read_b32 v243, v245 offset:1220
	ds_read_b32 v242, v244 offset:1220
	ds_read_b32 v239, v239 offset:1220
	s_waitcnt lgkmcnt(4)
	v_pk_add_f32 v[96:97], v[96:97], v[240:241]
	s_waitcnt lgkmcnt(3)
	v_pk_add_f32 v[94:95], v[94:95], v[236:237]
	v_pk_add_f32 v[92:93], v[92:93], v[232:233]
	v_pk_add_f32 v[90:91], v[90:91], v[146:147]
	v_pk_add_f32 v[88:89], v[88:89], v[142:143]
	v_pk_add_f32 v[86:87], v[86:87], v[138:139]
	v_pk_add_f32 v[84:85], v[84:85], v[134:135]
	v_pk_add_f32 v[82:83], v[82:83], v[98:99]
	s_waitcnt lgkmcnt(1)
	v_pk_add_f32 v[80:81], v[80:81], v[242:243]
	s_waitcnt lgkmcnt(0)
	v_pk_add_f32 v[78:79], v[78:79], v[238:239]
	v_pk_add_f32 v[76:77], v[76:77], v[234:235]
	v_pk_add_f32 v[74:75], v[74:75], v[230:231]
	v_pk_add_f32 v[72:73], v[72:73], v[144:145]
	v_pk_add_f32 v[70:71], v[70:71], v[140:141]
	v_pk_add_f32 v[68:69], v[68:69], v[136:137]
	v_pk_add_f32 v[66:67], v[66:67], v[132:133]
